# v13 combo + diff-attention pass-1 loops: Q-fragment vmcnt waits removed from the QK MFMAs (one vmcnt(0) before the loop instead) so K/V prefetch really runs two tiles ahead
# baseline (speedup 1.0000x reference)
; #define LAS __attribute__((address_space(3)))
; template <int DQK, int DK1, int DV, int MODE, bool QL = false> ...
;     ...
;     const int tid = ltid(), lane = tid & 63, r32 = lane & 31, hi = lane >> 5, wid = __builtin_amdgcn_readfirstlane(tid >> 6);
;     const int tq = q0 + 32 * wid + r32;
;     bf16x8 qf[DQK / 16];
; #pragma unroll
;     for (int d0 = 0; d0 < DQK / 16; ++d0) qf[d0] = gld((const bf16x8*)(Q + (size_t)tq * pitchQ + 16 * d0 + 8 * hi));
;     if constexpr (MODE == 2) {
;         bf16x8 x1 = qf[4], x2 = qf[5];
; #pragma unroll
;         for (int e = 0; e < 8; e += 2) {
;             const f32x2 cs0 = gld(rope + tq * 16 + 8 * hi + e), cs1 = gld(rope + tq * 16 + 8 * hi + e + 1);
;             const float a0 = bf1((bf16_t)x1[e]), b0 = bf1((bf16_t)x2[e]), a1 = bf1((bf16_t)x1[e + 1]), b1 = bf1((bf16_t)x2[e + 1]);
;             const unsigned w1 = cvt_pk_bf16(a0 * cs0.x - b0 * cs0.y, a1 * cs1.x - b1 * cs1.y), w2 = cvt_pk_bf16(a0 * cs0.y + b0 * cs0.x, a1 * cs1.y + b1 * cs1.x);
;             x1[e] = (short)(w1 & 0xffff); x1[e + 1] = (short)(w1 >> 16); x2[e] = (short)(w2 & 0xffff); x2[e + 1] = (short)(w2 >> 16);
;         }
;         qf[4] = x1; qf[5] = x2;
;     }
;     LAS unsigned char* qaddr = lds + QOFF + (wid * 32 + r32) * PK + hi * 16;
;     if constexpr (QL) {
; #pragma unroll
;         for (int d0 = 0; d0 < DQK / 16; ++d0) *(LAS bf16x8*)(qaddr + d0 * 32) = qf[d0];
;     }
;     constexpr bool D2 = true;
;     u32x4 kregA[N1], kreg2A, vregA[NV], kregB[D2 ? N1 : 1], kreg2B, vregB[D2 ? NV : 1];
;     ...
;     const int NT = (q0 + 256) / 64, tlast = q0 / 64 + (wid >> 1);
;     ATT_LOAD(A, NT - 1); ATT_WRITE(A, 0); if constexpr (D2) ATT_LOAD(A, NT - 2); __syncthreads();
;     float m_run = 0.f, l_run = 0.f;
; #pragma unroll
;     for (int db = 0; db < DV / 32; ++db)
; #pragma unroll
;         for (int r = 0; r < 16; ++r) o[db][r] = 0.f;
;     const int kfoff = r32 * PK + hi * 16;
;     const int vfoff = (4 * hi + ((lane & 15) >> 2)) * PV + (16 * ((lane >> 4) & 1) + 4 * (lane & 3)) * 2;
; __global__ void __launch_bounds__(512, 2) mega(Args a) {
;     ...
;                         const int b = v >> 2, h = v & 3; bf16_t* base = PROJ + (size_t)b * SEQ * INP;
;                         const float slope2 = __builtin_amdgcn_exp2f(-(float)(2 * h + 1)) * LOG2E, c2 = 0.125f * LOG2E;
;                         f32x16 o1[4]; float l0, l1; unsigned o0p[4][8];
.LBB0_654:
	s_ashr_i32 s40, s48, 2
	s_and_b32 s4, s48, 3
	s_mul_i32 s6, s40, 0x1b00000
	s_mul_hi_i32 s5, s40, 0x1b00000
	s_add_u32 s6, s10, s6
	s_addc_u32 s5, s11, s5
	s_lshl_b32 s7, s4, 1
	s_or_b32 s16, s7, 1
	s_lshl_b32 s7, s4, 8
	s_add_u32 s6, s6, s7
	s_addc_u32 s5, s5, 0
	s_add_u32 s50, s6, 0x1800
	s_addc_u32 s51, s5, 0
	s_add_u32 s14, s6, 0x1c00
	s_addc_u32 s15, s5, 0
	v_mov_b32_e32 v32, v182
	s_add_u32 s46, s6, 0x2000
	s_addc_u32 s47, s5, 0
	v_readfirstlane_b32 s17, v32
	v_and_b32_e32 v170, 31, v32
	s_ashr_i32 s5, s17, 1
	v_add_u32_e32 v10, 0x200, v32
	s_andn2_b32 s5, s5, 31
	v_or_b32_e32 v0, s64, v170
	v_ashrrev_i32_e32 v2, 31, v32
	v_ashrrev_i32_e32 v11, 31, v10
	v_add_u32_e32 v4, s5, v0
	v_lshrrev_b32_e32 v0, 29, v2
	v_lshrrev_b32_e32 v2, 28, v2
	v_lshrrev_b32_e32 v11, 28, v11
	v_add_u32_e32 v0, v32, v0
	v_add_u32_e32 v2, v32, v2
	v_add_u32_e32 v11, v10, v11
	v_ashrrev_i32_e32 v162, 3, v0
	v_and_b32_e32 v0, -8, v0
	v_ashrrev_i32_e32 v163, 4, v2
	v_and_b32_e32 v2, -16, v2
	v_ashrrev_i32_e32 v164, 4, v11
	v_and_b32_e32 v11, -16, v11
	v_sub_u32_e32 v34, v32, v0
	v_sub_u32_e32 v35, v32, v2
	v_sub_u32_e32 v36, v10, v11
	s_sub_i32 s59, 0x7c0, s53
	v_lshlrev_b32_e32 v18, 3, v34
	v_lshlrev_b32_e32 v24, 3, v35
	v_lshlrev_b32_e32 v28, 3, v36
	v_bfe_u32 v33, v32, 5, 1
	v_mov_b64_e32 v[14:15], s[50:51]
	v_add_u32_e32 v0, s59, v162
	v_mov_b64_e32 v[16:17], s[14:15]
	v_ashrrev_i32_e32 v19, 31, v18
	v_add_u32_e32 v2, s59, v163
	v_mov_b64_e32 v[22:23], s[46:47]
	v_ashrrev_i32_e32 v25, 31, v24
	v_add_u32_e32 v10, s59, v164
	v_ashrrev_i32_e32 v29, 31, v28
	v_mad_i64_i32 v[0:1], s[6:7], v0, s81, v[16:17]
	v_lshlrev_b64 v[20:21], 1, v[18:19]
	v_mad_i64_i32 v[2:3], s[6:7], v2, s81, v[22:23]
	v_lshlrev_b64 v[26:27], 1, v[24:25]
	v_mad_i64_i32 v[10:11], s[6:7], v10, s81, v[22:23]
	v_lshlrev_b64 v[30:31], 1, v[28:29]
	v_mad_i64_i32 v[14:15], s[6:7], v4, s81, v[14:15]
	v_lshlrev_b32_e32 v4, 4, v33
	v_lshl_add_u64 v[0:1], v[0:1], 0, v[20:21]
	v_lshl_add_u64 v[6:7], v[2:3], 0, v[26:27]
	v_lshl_add_u64 v[10:11], v[10:11], 0, v[30:31]
	v_lshl_add_u64 v[14:15], v[14:15], 0, v[4:5]
	s_sub_i32 s58, 0x780, s53
	global_load_dwordx4 v[0:3], v[0:1], off
	s_nop 0
	global_load_dwordx4 v[6:9], v[6:7], off
	s_sub_i32 s53, 0x800, s53
	global_load_dwordx4 v[10:13], v[10:11], off
	s_nop 0
	global_load_dwordx4 v[112:115], v[14:15], off
	global_load_dwordx4 v[116:119], v[14:15], off offset:32
	global_load_dwordx4 v[120:123], v[14:15], off offset:64
	global_load_dwordx4 v[124:127], v[14:15], off offset:96
	v_add_u32_e32 v14, s58, v162
	v_mad_i64_i32 v[14:15], s[6:7], v14, s81, v[16:17]
	v_lshl_add_u64 v[14:15], v[14:15], 0, v[20:21]
	global_load_dwordx4 v[128:131], v[14:15], off
	v_add_u32_e32 v14, s58, v163
	v_mad_i64_i32 v[14:15], s[6:7], v14, s81, v[22:23]
	v_add_u32_e32 v16, s58, v164
	v_lshl_add_u64 v[14:15], v[14:15], 0, v[26:27]
	v_mad_i64_i32 v[16:17], s[6:7], v16, s81, v[22:23]
	v_lshl_add_u64 v[16:17], v[16:17], 0, v[30:31]
	global_load_dwordx4 v[132:135], v[14:15], off
	global_load_dwordx4 v[136:139], v[16:17], off
	v_cvt_f32_ubyte0_e32 v14, s16
	v_exp_f32_e64 v14, -v14
	s_movk_i32 s6, 0x90
	v_lshlrev_b32_e32 v15, 4, v34
	s_ashr_i32 s57, s53, 6
	v_mul_f32_e32 v154, 0x3fb8aa3b, v14
	v_mul_lo_u32 v14, v162, s6
	s_movk_i32 s6, 0x140
	v_add3_u32 v165, 0, v14, v15
	v_mul_lo_u32 v173, v163, s6
	s_ashr_i32 s60, s17, 7
	s_ashr_i32 s56, s64, 6
	v_lshlrev_b32_e32 v171, 4, v35
	v_mul_lo_u32 v177, v164, s6
	v_lshlrev_b32_e32 v176, 2, v33
	v_lshlrev_b32_e32 v172, 4, v36
	s_add_i32 s60, s60, s56
	s_add_i32 s7, s57, -1
	s_cmp_gt_i32 s57, s56
	s_cselect_b64 s[48:49], -1, 0
	s_cmp_le_i32 s57, s56
	v_lshl_add_u64 v[156:157], v[18:19], 1, s[14:15]
	v_mul_f32_e32 v153, 0x42000000, v154
	v_lshl_add_u64 v[158:159], v[24:25], 1, s[46:47]
	v_lshl_add_u64 v[160:161], v[28:29], 1, s[46:47]
	s_waitcnt vmcnt(9)
	ds_write_b128 v165, v[0:3]
	v_add_u32_e32 v0, 0, v173
	v_lshrrev_b32_e32 v1, 2, v32
	v_and_b32_e32 v2, 16, v32
	v_lshlrev_b32_e32 v3, 2, v32
	v_add_u32_e32 v178, v0, v171
	v_add_u32_e32 v0, 0, v177
	v_and_or_b32 v1, v1, 3, v176
	v_and_or_b32 v2, v3, 12, v2
	v_add_u32_e32 v179, v0, v172
	v_mul_u32_u24_e32 v0, 0x90, v170
	v_mul_u32_u24_e32 v1, 0x140, v1
	v_lshlrev_b32_e32 v2, 1, v2
	v_add3_u32 v166, 0, v4, v0
	v_add3_u32 v167, 0, v1, v2
	s_waitcnt vmcnt(8)
	ds_write_b128 v178, v[6:9] offset:18432
	s_waitcnt vmcnt(7)
	ds_write_b128 v179, v[10:13] offset:18432
	s_waitcnt lgkmcnt(0)
	s_barrier
	s_cbranch_scc1 .LBB0_678
	s_lshl_b32 s16, s28, 8
	s_add_i32 s16, s16, s5
	s_addk_i32 s16, 0x740
	v_add_u32_e32 v0, s16, v170
	v_sub_u32_e32 v0, v0, v176
	v_subrev_u32_e32 v0, s53, v0
	s_lshl_b32 s16, s29, 8
	v_mov_b32_e32 v14, v5
	v_mov_b32_e32 v15, v5
	v_subrev_u32_e32 v180, s16, v0
	v_mov_b32_e32 v0, v5
	v_mov_b32_e32 v1, v5
	v_mov_b32_e32 v2, v5
	v_mov_b32_e32 v3, v5
	v_mov_b32_e32 v4, v5
	v_mov_b32_e32 v6, v5
	v_mov_b32_e32 v7, v5
	v_mov_b32_e32 v8, v5
	v_mov_b32_e32 v9, v5
	v_mov_b32_e32 v10, v5
	v_mov_b32_e32 v11, v5
	v_mov_b32_e32 v12, v5
	v_mov_b32_e32 v13, v5
	v_mov_b64_e32 v[78:79], v[14:15]
	v_mov_b64_e32 v[62:63], v[14:15]
	v_mov_b64_e32 v[46:47], v[14:15]
	v_mov_b64_e32 v[30:31], v[14:15]
	v_mov_b32_e32 v155, v154
	s_sub_i32 s6, 0, s60
	s_add_i32 s22, s57, -2
	v_mov_b32_e32 v169, 0
	v_mov_b32_e32 v181, v162
	v_mov_b32_e32 v204, v163
	v_mov_b32_e32 v205, v164
	v_mov_b64_e32 v[76:77], v[12:13]
	v_mov_b64_e32 v[74:75], v[10:11]
	v_mov_b64_e32 v[72:73], v[8:9]
	v_mov_b64_e32 v[70:71], v[6:7]
	v_mov_b64_e32 v[68:69], v[4:5]
	v_mov_b64_e32 v[66:67], v[2:3]
	v_mov_b64_e32 v[64:65], v[0:1]
	v_mov_b64_e32 v[60:61], v[12:13]
	v_mov_b64_e32 v[58:59], v[10:11]
	v_mov_b64_e32 v[56:57], v[8:9]
	v_mov_b64_e32 v[54:55], v[6:7]
	v_mov_b64_e32 v[52:53], v[4:5]
	v_mov_b64_e32 v[50:51], v[2:3]
	v_mov_b64_e32 v[48:49], v[0:1]
	v_mov_b64_e32 v[44:45], v[12:13]
	v_mov_b64_e32 v[42:43], v[10:11]
	v_mov_b64_e32 v[40:41], v[8:9]
	v_mov_b64_e32 v[38:39], v[6:7]
	v_mov_b64_e32 v[36:37], v[4:5]
	v_mov_b64_e32 v[34:35], v[2:3]
	v_mov_b64_e32 v[32:33], v[0:1]
	v_mov_b64_e32 v[28:29], v[12:13]
	v_mov_b64_e32 v[26:27], v[10:11]
	v_mov_b64_e32 v[24:25], v[8:9]
	v_mov_b64_e32 v[22:23], v[6:7]
	v_mov_b64_e32 v[20:21], v[4:5]
	v_mov_b64_e32 v[18:19], v[2:3]
	v_mov_b64_e32 v[16:17], v[0:1]
	v_mov_b32_e32 v168, 0
	s_waitcnt vmcnt(0)

.LBB0_667:
	v_cvt_f32_i32_e32 v4, v180
	s_cmp_eq_u32 s23, -1
	s_cselect_b64 s[18:19], -1, 0
	v_cndmask_b32_e64 v3, v169, 0, s[18:19]
	v_fma_f32 v4, -v154, v4, -v3
	s_mov_b32 s20, 2.0
	v_add_f32_e32 v6, v153, v4
	s_mov_b32 s21, 0x40400000
	v_pk_fma_f32 v[98:99], v[154:155], s[20:21], v[4:5] op_sel_hi:[1,1,0]
	v_pk_fma_f32 v[82:83], v[154:155], s[20:21], v[6:7] op_sel_hi:[1,1,0]
	s_mov_b32 s20, 0x41200000
	s_mov_b32 s21, 0x41300000
	v_pk_fma_f32 v[102:103], v[154:155], s[20:21], v[4:5] op_sel_hi:[1,1,0]
	v_pk_fma_f32 v[86:87], v[154:155], s[20:21], v[6:7] op_sel_hi:[1,1,0]
	s_mov_b32 s20, 0x41800000
	s_mov_b32 s21, 0x41880000
	v_pk_fma_f32 v[104:105], v[154:155], s[20:21], v[4:5] op_sel_hi:[1,1,0]
	v_pk_fma_f32 v[88:89], v[154:155], s[20:21], v[6:7] op_sel_hi:[1,1,0]
	s_mov_b32 s20, 0x41900000
	s_mov_b32 s21, 0x41980000
	v_fma_f32 v80, 0, v154, v6
	v_add_f32_e32 v81, v154, v6
	v_pk_fma_f32 v[84:85], v[154:155], s[38:39], v[6:7] op_sel_hi:[1,1,0]
	v_pk_fma_f32 v[90:91], v[154:155], s[20:21], v[6:7] op_sel_hi:[1,1,0]
	v_pk_fma_f32 v[92:93], v[154:155], s[26:27], v[6:7] op_sel_hi:[1,1,0]
	v_pk_fma_f32 v[94:95], v[154:155], s[36:37], v[6:7] op_sel_hi:[1,1,0]
	ds_read_b128 v[6:9], v166 offset:4608
	ds_read_b128 v[10:13], v166
	ds_read_b128 v[206:209], v166 offset:32
	v_fma_f32 v96, 0, v154, v4
	v_add_f32_e32 v97, v154, v4
	v_pk_fma_f32 v[100:101], v[154:155], s[38:39], v[4:5] op_sel_hi:[1,1,0]
	v_pk_fma_f32 v[106:107], v[154:155], s[20:21], v[4:5] op_sel_hi:[1,1,0]
	v_pk_fma_f32 v[108:109], v[154:155], s[26:27], v[4:5] op_sel_hi:[1,1,0]
	v_pk_fma_f32 v[110:111], v[154:155], s[36:37], v[4:5] op_sel_hi:[1,1,0]
	s_waitcnt lgkmcnt(2)
	v_mfma_f32_32x32x16_bf16 v[80:95], v[6:9], v[112:115], v[80:95]
	ds_read_b128 v[6:9], v166 offset:4640
	v_cmp_lt_i32_e32 vcc, 0, v180
	s_mov_b64 s[20:21], s[18:19]
	s_waitcnt lgkmcnt(2)
	v_mfma_f32_32x32x16_bf16 v[96:111], v[10:13], v[112:115], v[96:111]
	s_waitcnt lgkmcnt(1)
	v_mfma_f32_32x32x16_bf16 v[96:111], v[206:209], v[116:119], v[96:111]
	s_waitcnt lgkmcnt(0)
	v_mfma_f32_32x32x16_bf16 v[80:95], v[6:9], v[116:119], v[80:95]
	ds_read_b128 v[6:9], v166 offset:64
	ds_read_b128 v[10:13], v166 offset:4672
	s_waitcnt lgkmcnt(1)
	v_mfma_f32_32x32x16_bf16 v[96:111], v[6:9], v[120:123], v[96:111]
	s_waitcnt lgkmcnt(0)
	v_mfma_f32_32x32x16_bf16 v[80:95], v[10:13], v[120:123], v[80:95]
	ds_read_b128 v[6:9], v166 offset:96
	ds_read_b128 v[10:13], v166 offset:4704
	s_waitcnt lgkmcnt(1)
	v_mfma_f32_32x32x16_bf16 v[96:111], v[6:9], v[124:127], v[96:111]
	s_waitcnt lgkmcnt(0)
	v_mfma_f32_32x32x16_bf16 v[80:95], v[10:13], v[124:127], v[80:95]
	s_nop 9
	v_cndmask_b32_e32 v4, v196, v97, vcc
	v_cmp_lt_i32_e32 vcc, -1, v180
	s_nop 1
	v_cndmask_b32_e32 v211, v196, v96, vcc
	v_cmp_lt_i32_e32 vcc, 32, v180
	s_nop 1
	v_cndmask_b32_e32 v210, v196, v81, vcc
	v_cmp_lt_i32_e32 vcc, 31, v180
	s_nop 1
	v_cndmask_b32_e32 v212, v196, v80, vcc
	v_cmp_lt_i32_e32 vcc, 2, v180
	s_nop 1
	v_cndmask_b32_e32 v206, v196, v99, vcc
	v_cmp_lt_i32_e32 vcc, 1, v180
	s_nop 1
	v_cndmask_b32_e32 v208, v196, v98, vcc
	v_cmp_lt_i32_e32 vcc, 34, v180
	s_nop 1
	v_cndmask_b32_e32 v207, v196, v83, vcc
	v_cmp_lt_i32_e32 vcc, 33, v180
	s_nop 1
	v_cndmask_b32_e32 v209, v196, v82, vcc
	v_cmp_lt_i32_e32 vcc, 8, v180
	s_nop 1
	v_cndmask_b32_e32 v97, v196, v101, vcc
	v_cmp_lt_i32_e32 vcc, 7, v180
	s_nop 1
	v_cndmask_b32_e32 v99, v196, v100, vcc
	v_cmp_lt_i32_e32 vcc, 40, v180
	s_nop 1
	v_cndmask_b32_e32 v98, v196, v85, vcc
	v_cmp_lt_i32_e32 vcc, 39, v180
	s_nop 1
	v_cndmask_b32_e32 v100, v196, v84, vcc
	v_cmp_lt_i32_e32 vcc, 10, v180
	s_nop 1
	v_cndmask_b32_e32 v84, v196, v103, vcc
	v_cmp_lt_i32_e32 vcc, 9, v180
	s_nop 1
	v_cndmask_b32_e32 v96, v196, v102, vcc
	v_cmp_lt_i32_e32 vcc, 42, v180
	s_nop 1
	v_cndmask_b32_e32 v87, v196, v87, vcc
	v_cmp_lt_i32_e32 vcc, 41, v180
	s_nop 1
	v_cndmask_b32_e32 v86, v196, v86, vcc
	v_cmp_lt_i32_e32 vcc, 16, v180
	s_nop 1
	v_cndmask_b32_e32 v80, v196, v105, vcc
	v_cmp_lt_i32_e32 vcc, 15, v180
	s_nop 1
	v_cndmask_b32_e32 v83, v196, v104, vcc
	v_cmp_lt_i32_e32 vcc, 48, v180
	s_nop 1
	v_cndmask_b32_e32 v82, v196, v89, vcc
	v_cmp_lt_i32_e32 vcc, 47, v180
	v_max_f32_e32 v89, v210, v210
	s_nop 0
	v_cndmask_b32_e32 v85, v196, v88, vcc
	v_cmp_lt_i32_e32 vcc, 18, v180
	v_max_f32_e32 v88, v4, v4
	v_max_f32_e32 v88, v88, v89
	v_cndmask_b32_e32 v12, v196, v107, vcc
	v_cmp_lt_i32_e32 vcc, 17, v180
	v_max_f32_e32 v89, v208, v208
	v_max3_f32 v88, v211, v212, v88
	v_cndmask_b32_e32 v15, v196, v106, vcc
	v_cmp_lt_i32_e32 vcc, 50, v180
	s_nop 1
	v_cndmask_b32_e32 v14, v196, v91, vcc
	v_cmp_lt_i32_e32 vcc, 49, v180
	v_max_f32_e32 v91, v207, v207
	s_nop 0
	v_cndmask_b32_e32 v81, v196, v90, vcc
	v_max_f32_e32 v90, v209, v209
	v_max_f32_e32 v89, v89, v90
	v_max_f32_e32 v90, v206, v206
	v_max_f32_e32 v90, v90, v91
	v_max3_f32 v88, v88, v89, v90
	v_max_f32_e32 v89, v99, v99
	v_max_f32_e32 v90, v100, v100
	v_max_f32_e32 v89, v89, v90
	v_max_f32_e32 v90, v97, v97
	v_max_f32_e32 v91, v98, v98
	v_max_f32_e32 v90, v90, v91
	v_max3_f32 v88, v88, v89, v90
	v_max_f32_e32 v89, v96, v96
	v_max_f32_e32 v90, v86, v86
	v_max_f32_e32 v89, v89, v90
	v_max_f32_e32 v90, v84, v84
	v_max_f32_e32 v91, v87, v87
	v_max_f32_e32 v90, v90, v91
	v_cmp_lt_i32_e32 vcc, 24, v180
	v_max3_f32 v88, v88, v89, v90
	v_max_f32_e32 v89, v83, v83
	v_max_f32_e32 v90, v85, v85
	v_cndmask_b32_e32 v8, v196, v109, vcc
	v_cmp_lt_i32_e32 vcc, 23, v180
	v_max_f32_e32 v89, v89, v90
	v_max_f32_e32 v90, v80, v80
	v_max_f32_e32 v91, v82, v82
	v_cndmask_b32_e32 v11, v196, v108, vcc
	v_cmp_lt_i32_e32 vcc, 56, v180
	v_max_f32_e32 v90, v90, v91
	v_max3_f32 v88, v88, v89, v90
	v_cndmask_b32_e32 v10, v196, v93, vcc
	v_cmp_lt_i32_e32 vcc, 55, v180
	v_max_f32_e32 v89, v15, v15
	v_max_f32_e32 v90, v81, v81
	v_cndmask_b32_e32 v13, v196, v92, vcc
	v_cmp_lt_i32_e32 vcc, 26, v180
	v_max_f32_e32 v89, v89, v90
	v_max_f32_e32 v90, v12, v12
	v_max_f32_e32 v91, v14, v14
	v_cndmask_b32_e32 v3, v196, v111, vcc
	v_cmp_lt_i32_e32 vcc, 25, v180
	v_max_f32_e32 v90, v90, v91
	v_max3_f32 v88, v88, v89, v90
	v_cndmask_b32_e32 v7, v196, v110, vcc
	v_cmp_lt_i32_e32 vcc, 58, v180
	v_max_f32_e32 v89, v11, v11
	v_max_f32_e32 v90, v13, v13
	v_cndmask_b32_e32 v6, v196, v95, vcc
	v_cmp_lt_i32_e32 vcc, 57, v180
	v_max_f32_e32 v89, v89, v90
	v_max_f32_e32 v90, v8, v8
	v_max_f32_e32 v91, v10, v10
	v_cndmask_b32_e32 v9, v196, v94, vcc
	v_max_f32_e32 v90, v90, v91
	v_max3_f32 v88, v88, v89, v90
	v_max_f32_e32 v89, v7, v7
	v_max_f32_e32 v90, v9, v9
	v_max_f32_e32 v89, v89, v90
	v_max_f32_e32 v90, v3, v3
	v_max_f32_e32 v91, v6, v6
	v_max_f32_e32 v90, v90, v91
	v_max3_f32 v88, v88, v89, v90
	ds_bpermute_b32 v89, v174, v88
	s_and_b64 vcc, exec, s[18:19]
	s_waitcnt lgkmcnt(0)
	v_max_f32_e32 v89, v89, v89
	v_max_f32_e32 v88, v88, v89
	v_cmp_lt_f32_e64 s[44:45], s38, v88
	s_cbranch_vccnz .LBB0_669
	s_cmp_lg_u64 s[44:45], 0
	s_cselect_b64 s[20:21], -1, 0

.LBB0_673:
	v_add_u32_e32 v212, 64, v180
	v_cvt_f32_i32_e32 v1, v212
	s_cmp_eq_u32 s23, 0
	s_cselect_b64 s[18:19], -1, 0
	v_cndmask_b32_e64 v0, v169, 0, s[18:19]
	v_fma_f32 v0, -v154, v1, -v0
	s_mov_b32 s20, 2.0
	v_add_f32_e32 v2, v153, v0
	s_mov_b32 s21, 0x40400000
	v_pk_fma_f32 v[98:99], v[154:155], s[20:21], v[0:1] op_sel_hi:[1,1,0]
	v_pk_fma_f32 v[82:83], v[154:155], s[20:21], v[2:3] op_sel_hi:[1,1,0]
	s_mov_b32 s20, 0x41200000
	s_mov_b32 s21, 0x41300000
	v_pk_fma_f32 v[102:103], v[154:155], s[20:21], v[0:1] op_sel_hi:[1,1,0]
	v_pk_fma_f32 v[86:87], v[154:155], s[20:21], v[2:3] op_sel_hi:[1,1,0]
	s_mov_b32 s20, 0x41800000
	s_mov_b32 s21, 0x41880000
	v_pk_fma_f32 v[104:105], v[154:155], s[20:21], v[0:1] op_sel_hi:[1,1,0]
	v_pk_fma_f32 v[88:89], v[154:155], s[20:21], v[2:3] op_sel_hi:[1,1,0]
	s_mov_b32 s20, 0x41900000
	s_mov_b32 s21, 0x41980000
	v_fma_f32 v96, 0, v154, v0
	v_fma_f32 v80, 0, v154, v2
	v_add_f32_e32 v97, v154, v0
	v_add_f32_e32 v81, v154, v2
	v_pk_fma_f32 v[100:101], v[154:155], s[38:39], v[0:1] op_sel_hi:[1,1,0]
	v_pk_fma_f32 v[84:85], v[154:155], s[38:39], v[2:3] op_sel_hi:[1,1,0]
	v_pk_fma_f32 v[106:107], v[154:155], s[20:21], v[0:1] op_sel_hi:[1,1,0]
	v_pk_fma_f32 v[90:91], v[154:155], s[20:21], v[2:3] op_sel_hi:[1,1,0]
	v_pk_fma_f32 v[108:109], v[154:155], s[26:27], v[0:1] op_sel_hi:[1,1,0]
	v_pk_fma_f32 v[92:93], v[154:155], s[26:27], v[2:3] op_sel_hi:[1,1,0]
	v_pk_fma_f32 v[110:111], v[154:155], s[36:37], v[0:1] op_sel_hi:[1,1,0]
	v_pk_fma_f32 v[94:95], v[154:155], s[36:37], v[2:3] op_sel_hi:[1,1,0]
	ds_read_b128 v[0:3], v166 offset:13824
	ds_read_b128 v[6:9], v166 offset:9216
	ds_read_b128 v[10:13], v166 offset:9248
	s_waitcnt lgkmcnt(1)
	v_mfma_f32_32x32x16_bf16 v[96:111], v[6:9], v[112:115], v[96:111]
	v_cmp_lt_i32_e32 vcc, 0, v212
	s_mov_b64 s[20:21], s[18:19]
	v_mfma_f32_32x32x16_bf16 v[80:95], v[0:3], v[112:115], v[80:95]
	ds_read_b128 v[0:3], v166 offset:13856
	s_waitcnt lgkmcnt(1)
	v_mfma_f32_32x32x16_bf16 v[96:111], v[10:13], v[116:119], v[96:111]
	s_waitcnt lgkmcnt(0)
	v_mfma_f32_32x32x16_bf16 v[80:95], v[0:3], v[116:119], v[80:95]
	ds_read_b128 v[0:3], v166 offset:9280
	ds_read_b128 v[6:9], v166 offset:13888
	s_waitcnt lgkmcnt(1)
	v_mfma_f32_32x32x16_bf16 v[96:111], v[0:3], v[120:123], v[96:111]
	s_waitcnt lgkmcnt(0)
	v_mfma_f32_32x32x16_bf16 v[80:95], v[6:9], v[120:123], v[80:95]
	ds_read_b128 v[0:3], v166 offset:9312
	ds_read_b128 v[6:9], v166 offset:13920
	s_waitcnt lgkmcnt(1)
	v_mfma_f32_32x32x16_bf16 v[96:111], v[0:3], v[124:127], v[96:111]
	s_waitcnt lgkmcnt(0)
	v_mfma_f32_32x32x16_bf16 v[80:95], v[6:9], v[124:127], v[80:95]
	s_nop 9
	v_cndmask_b32_e32 v4, v196, v97, vcc
	v_cmp_lt_i32_e32 vcc, -1, v212
	s_nop 1
	v_cndmask_b32_e32 v210, v196, v96, vcc
	v_cmp_lt_i32_e32 vcc, 32, v212
	s_nop 1
	v_cndmask_b32_e32 v209, v196, v81, vcc
	v_cmp_lt_i32_e32 vcc, 31, v212
	s_nop 1
	v_cndmask_b32_e32 v211, v196, v80, vcc
	v_cmp_lt_i32_e32 vcc, 2, v212
	s_nop 1
	v_cndmask_b32_e32 v99, v196, v99, vcc
	v_cmp_lt_i32_e32 vcc, 1, v212
	s_nop 1
	v_cndmask_b32_e32 v207, v196, v98, vcc
	v_cmp_lt_i32_e32 vcc, 34, v212
	s_nop 1
	v_cndmask_b32_e32 v206, v196, v83, vcc
	v_cmp_lt_i32_e32 vcc, 33, v212
	s_nop 1
	v_cndmask_b32_e32 v208, v196, v82, vcc
	v_cmp_lt_i32_e32 vcc, 8, v212
	s_nop 1
	v_cndmask_b32_e32 v96, v196, v101, vcc
	v_cmp_lt_i32_e32 vcc, 7, v212
	s_nop 1
	v_cndmask_b32_e32 v98, v196, v100, vcc
	v_cmp_lt_i32_e32 vcc, 40, v212
	s_nop 1
	v_cndmask_b32_e32 v97, v196, v85, vcc
	v_cmp_lt_i32_e32 vcc, 39, v212
	s_nop 1
	v_cndmask_b32_e32 v100, v196, v84, vcc
	v_cmp_lt_i32_e32 vcc, 10, v212
	s_nop 1
	v_cndmask_b32_e32 v81, v196, v103, vcc
	v_cmp_lt_i32_e32 vcc, 9, v212
	s_nop 1
	v_cndmask_b32_e32 v84, v196, v102, vcc
	v_cmp_lt_i32_e32 vcc, 42, v212
	s_nop 1
	v_cndmask_b32_e32 v83, v196, v87, vcc
	v_cmp_lt_i32_e32 vcc, 41, v212
	v_max_f32_e32 v87, v209, v209
	s_nop 0
	v_cndmask_b32_e32 v85, v196, v86, vcc
	v_cmp_lt_i32_e32 vcc, 16, v212
	v_max_f32_e32 v86, v4, v4
	v_max_f32_e32 v86, v86, v87
	v_cndmask_b32_e32 v13, v196, v105, vcc
	v_cmp_lt_i32_e32 vcc, 15, v212
	v_max_f32_e32 v87, v207, v207
	v_max3_f32 v86, v210, v211, v86
	v_cndmask_b32_e32 v80, v196, v104, vcc
	v_cmp_lt_i32_e32 vcc, 48, v212
	s_nop 1
	v_cndmask_b32_e32 v15, v196, v89, vcc
	v_cmp_lt_i32_e32 vcc, 47, v212
	v_max_f32_e32 v89, v206, v206
	s_nop 0
	v_cndmask_b32_e32 v82, v196, v88, vcc
	v_max_f32_e32 v88, v208, v208
	v_max_f32_e32 v87, v87, v88
	v_max_f32_e32 v88, v99, v99
	v_max_f32_e32 v88, v88, v89
	v_max3_f32 v86, v86, v87, v88
	v_max_f32_e32 v87, v98, v98
	v_max_f32_e32 v88, v100, v100
	v_max_f32_e32 v87, v87, v88
	v_max_f32_e32 v88, v96, v96
	v_max_f32_e32 v89, v97, v97
	v_cmp_lt_i32_e32 vcc, 18, v212
	v_max_f32_e32 v88, v88, v89
	v_max3_f32 v86, v86, v87, v88
	v_cndmask_b32_e32 v9, v196, v107, vcc
	v_cmp_lt_i32_e32 vcc, 17, v212
	v_max_f32_e32 v87, v84, v84
	v_max_f32_e32 v88, v85, v85
	v_cndmask_b32_e32 v12, v196, v106, vcc
	v_cmp_lt_i32_e32 vcc, 50, v212
	v_max_f32_e32 v87, v87, v88
	v_max_f32_e32 v88, v81, v81
	v_max_f32_e32 v89, v83, v83
	v_cndmask_b32_e32 v11, v196, v91, vcc
	v_cmp_lt_i32_e32 vcc, 49, v212
	v_max_f32_e32 v88, v88, v89
	v_max3_f32 v86, v86, v87, v88
	v_cndmask_b32_e32 v14, v196, v90, vcc
	v_cmp_lt_i32_e32 vcc, 24, v212
	v_max_f32_e32 v87, v80, v80
	v_max_f32_e32 v88, v82, v82
	v_cndmask_b32_e32 v3, v196, v109, vcc
	v_cmp_lt_i32_e32 vcc, 23, v212
	v_max_f32_e32 v87, v87, v88
	v_max_f32_e32 v88, v13, v13
	v_max_f32_e32 v89, v15, v15
	v_cndmask_b32_e32 v8, v196, v108, vcc
	v_cmp_lt_i32_e32 vcc, 56, v212
	v_max_f32_e32 v88, v88, v89
	v_max3_f32 v86, v86, v87, v88
	v_cndmask_b32_e32 v7, v196, v93, vcc
	v_cmp_lt_i32_e32 vcc, 55, v212
	v_max_f32_e32 v87, v12, v12
	v_max_f32_e32 v88, v14, v14
	v_cndmask_b32_e32 v10, v196, v92, vcc
	v_cmp_lt_i32_e32 vcc, 26, v212
	v_max_f32_e32 v87, v87, v88
	v_max_f32_e32 v88, v9, v9
	v_max_f32_e32 v89, v11, v11
	v_cndmask_b32_e32 v0, v196, v111, vcc
	v_cmp_lt_i32_e32 vcc, 25, v212
	v_max_f32_e32 v88, v88, v89
	v_max3_f32 v86, v86, v87, v88
	v_cndmask_b32_e32 v2, v196, v110, vcc
	v_cmp_lt_i32_e32 vcc, 58, v212
	v_max_f32_e32 v87, v8, v8
	v_max_f32_e32 v88, v10, v10
	v_cndmask_b32_e32 v1, v196, v95, vcc
	v_cmp_lt_i32_e32 vcc, 57, v212
	v_max_f32_e32 v87, v87, v88
	v_max_f32_e32 v88, v3, v3
	v_max_f32_e32 v89, v7, v7
	v_cndmask_b32_e32 v6, v196, v94, vcc
	v_max_f32_e32 v88, v88, v89
	v_max3_f32 v86, v86, v87, v88
	v_max_f32_e32 v87, v2, v2
	v_max_f32_e32 v88, v6, v6
	v_max_f32_e32 v87, v87, v88
	v_max_f32_e32 v88, v0, v0
	v_max_f32_e32 v89, v1, v1
	v_max_f32_e32 v88, v88, v89
	v_max3_f32 v86, v86, v87, v88
	ds_bpermute_b32 v87, v174, v86
	s_and_b64 vcc, exec, s[18:19]
	s_waitcnt lgkmcnt(0)
	v_max_f32_e32 v87, v87, v87
	v_max_f32_e32 v86, v86, v87
	v_cmp_lt_f32_e64 s[44:45], s38, v86
	s_cbranch_vccnz .LBB0_675
	s_cmp_lg_u64 s[44:45], 0
	s_cselect_b64 s[20:21], -1, 0

.LBB0_690:
	v_cvt_f32_i32_e32 v4, v0
	s_cmp_eq_u32 s60, s52
	s_cselect_b64 s[44:45], -1, 0
	v_cndmask_b32_e64 v10, v169, 0, s[44:45]
	v_add_u32_e32 v14, s4, v166
	v_fma_f32 v4, -v154, v4, -v10
	ds_read_b128 v[10:13], v14
	s_mov_b32 s20, 2.0
	s_mov_b32 s22, 0x41200000
	s_mov_b32 s24, 0x41800000
	s_mov_b32 s28, 0x41900000
	s_mov_b32 s21, 0x40400000
	s_mov_b32 s23, 0x41300000
	s_mov_b32 s25, 0x41880000
	s_mov_b32 s29, 0x41980000
	v_fma_f32 v80, 0, v154, v4
	v_add_f32_e32 v81, v154, v4
	v_pk_fma_f32 v[82:83], v[154:155], s[20:21], v[4:5] op_sel_hi:[1,1,0]
	v_pk_fma_f32 v[84:85], v[154:155], s[38:39], v[4:5] op_sel_hi:[1,1,0]
	v_pk_fma_f32 v[86:87], v[154:155], s[22:23], v[4:5] op_sel_hi:[1,1,0]
	v_pk_fma_f32 v[88:89], v[154:155], s[24:25], v[4:5] op_sel_hi:[1,1,0]
	v_pk_fma_f32 v[90:91], v[154:155], s[28:29], v[4:5] op_sel_hi:[1,1,0]
	v_pk_fma_f32 v[92:93], v[154:155], s[26:27], v[4:5] op_sel_hi:[1,1,0]
	v_pk_fma_f32 v[94:95], v[154:155], s[36:37], v[4:5] op_sel_hi:[1,1,0]
	v_add_f32_e32 v4, v153, v4
	v_fma_f32 v96, 0, v154, v4
	s_waitcnt lgkmcnt(0)
	v_mfma_f32_32x32x16_bf16 v[80:95], v[10:13], v[112:115], v[80:95]
	ds_read_b128 v[10:13], v14 offset:32
	v_add_f32_e32 v97, v154, v4
	v_fma_f32 v98, v154, s20, v4
	v_fma_f32 v99, v155, s21, v4
	v_fma_f32 v100, v154, s38, v4
	v_fma_f32 v101, v155, s39, v4
	v_pk_fma_f32 v[102:103], v[154:155], s[22:23], v[4:5] op_sel_hi:[1,1,0]
	v_pk_fma_f32 v[104:105], v[154:155], s[24:25], v[4:5] op_sel_hi:[1,1,0]
	v_pk_fma_f32 v[106:107], v[154:155], s[28:29], v[4:5] op_sel_hi:[1,1,0]
	s_waitcnt lgkmcnt(0)
	v_mfma_f32_32x32x16_bf16 v[80:95], v[10:13], v[116:119], v[80:95]
	ds_read_b128 v[10:13], v14 offset:64
	v_fma_f32 v108, v154, s26, v4
	v_fma_f32 v109, v155, s27, v4
	v_fma_f32 v110, v154, s36, v4
	v_fma_f32 v111, v155, s37, v4
	s_cmp_lg_u32 s60, s52
	s_waitcnt lgkmcnt(0)
	v_mfma_f32_32x32x16_bf16 v[80:95], v[10:13], v[120:123], v[80:95]
	ds_read_b128 v[10:13], v14 offset:96
	ds_read_b128 v[170:173], v14 offset:4608
	s_waitcnt lgkmcnt(1)
	v_mfma_f32_32x32x16_bf16 v[80:95], v[10:13], v[124:127], v[80:95]
	ds_read_b128 v[10:13], v14 offset:4640
	s_waitcnt lgkmcnt(1)
	v_mfma_f32_32x32x16_bf16 v[96:111], v[170:173], v[112:115], v[96:111]
	s_nop 8
	v_max_f32_e32 v4, v81, v81
	s_waitcnt lgkmcnt(0)
	v_mfma_f32_32x32x16_bf16 v[96:111], v[10:13], v[116:119], v[96:111]
	ds_read_b128 v[10:13], v14 offset:4672
	s_waitcnt lgkmcnt(0)
	v_mfma_f32_32x32x16_bf16 v[96:111], v[10:13], v[120:123], v[96:111]
	ds_read_b128 v[10:13], v14 offset:4704
	s_waitcnt lgkmcnt(0)
	v_mfma_f32_32x32x16_bf16 v[96:111], v[10:13], v[124:127], v[96:111]
	s_nop 11
	v_max3_f32 v10, v97, v82, v98
	v_max3_f32 v4, v4, v83, v99
	v_max3_f32 v10, v10, v80, v96
	v_max3_f32 v4, v4, v84, v100
	v_max3_f32 v10, v10, v85, v101
	v_max3_f32 v4, v4, v86, v102
	v_max3_f32 v10, v10, v87, v103
	v_max3_f32 v4, v4, v88, v104
	v_max3_f32 v10, v10, v89, v105
	v_max3_f32 v4, v4, v90, v106
	v_max3_f32 v10, v10, v91, v107
	v_max3_f32 v4, v4, v92, v108
	v_max3_f32 v10, v10, v93, v109
	v_max3_f32 v4, v4, v94, v110
	v_max3_f32 v10, v10, v95, v111
	v_max_f32_e32 v4, v4, v10
	ds_bpermute_b32 v10, v174, v4
	s_waitcnt lgkmcnt(0)
	v_max_f32_e32 v10, v10, v10
	v_max_f32_e32 v4, v4, v10
	v_cmp_lt_f32_e32 vcc, s38, v4
	s_cbranch_scc0 .LBB0_695
	s_cmp_lg_u64 vcc, 0
	s_cselect_b64 s[20:21], -1, 0
	s_cbranch_execz .LBB0_696
	s_branch .LBB0_697

.LBB0_693:
	v_add_u32_e32 v4, 64, v0
	v_cvt_f32_i32_e32 v4, v4
	s_cmp_eq_u32 s5, s52
	s_cselect_b64 s[44:45], -1, 0
	v_cndmask_b32_e64 v7, v169, 0, s[44:45]
	v_fma_f32 v4, -v154, v4, -v7
	v_add_u32_e32 v7, s62, v166
	ds_read_b128 v[8:11], v7
	s_mov_b32 s20, 2.0
	s_mov_b32 s22, 0x41200000
	s_mov_b32 s24, 0x41800000
	s_mov_b32 s28, 0x41900000
	s_mov_b32 s21, 0x40400000
	s_mov_b32 s23, 0x41300000
	s_mov_b32 s25, 0x41880000
	s_mov_b32 s29, 0x41980000
	v_fma_f32 v80, 0, v154, v4
	v_add_f32_e32 v81, v154, v4
	v_pk_fma_f32 v[82:83], v[154:155], s[20:21], v[4:5] op_sel_hi:[1,1,0]
	v_pk_fma_f32 v[84:85], v[154:155], s[38:39], v[4:5] op_sel_hi:[1,1,0]
	v_pk_fma_f32 v[86:87], v[154:155], s[22:23], v[4:5] op_sel_hi:[1,1,0]
	v_pk_fma_f32 v[88:89], v[154:155], s[24:25], v[4:5] op_sel_hi:[1,1,0]
	v_pk_fma_f32 v[90:91], v[154:155], s[28:29], v[4:5] op_sel_hi:[1,1,0]
	v_pk_fma_f32 v[92:93], v[154:155], s[26:27], v[4:5] op_sel_hi:[1,1,0]
	v_pk_fma_f32 v[94:95], v[154:155], s[36:37], v[4:5] op_sel_hi:[1,1,0]
	v_add_f32_e32 v4, v153, v4
	v_fma_f32 v96, 0, v154, v4
	s_waitcnt lgkmcnt(0)
	v_mfma_f32_32x32x16_bf16 v[80:95], v[8:11], v[112:115], v[80:95]
	ds_read_b128 v[8:11], v7 offset:32
	v_add_f32_e32 v97, v154, v4
	v_fma_f32 v98, v154, s20, v4
	v_fma_f32 v99, v155, s21, v4
	v_fma_f32 v100, v154, s38, v4
	v_fma_f32 v101, v155, s39, v4
	v_pk_fma_f32 v[102:103], v[154:155], s[22:23], v[4:5] op_sel_hi:[1,1,0]
	v_pk_fma_f32 v[104:105], v[154:155], s[24:25], v[4:5] op_sel_hi:[1,1,0]
	v_pk_fma_f32 v[106:107], v[154:155], s[28:29], v[4:5] op_sel_hi:[1,1,0]
	s_waitcnt lgkmcnt(0)
	v_mfma_f32_32x32x16_bf16 v[80:95], v[8:11], v[116:119], v[80:95]
	ds_read_b128 v[8:11], v7 offset:64
	v_fma_f32 v108, v154, s26, v4
	v_fma_f32 v109, v155, s27, v4
	v_fma_f32 v110, v154, s36, v4
	v_fma_f32 v111, v155, s37, v4
	s_cmp_lg_u32 s5, s52
	s_waitcnt lgkmcnt(0)
	v_mfma_f32_32x32x16_bf16 v[80:95], v[8:11], v[120:123], v[80:95]
	ds_read_b128 v[8:11], v7 offset:96
	ds_read_b128 v[12:15], v7 offset:4608
	s_waitcnt lgkmcnt(1)
	v_mfma_f32_32x32x16_bf16 v[80:95], v[8:11], v[124:127], v[80:95]
	ds_read_b128 v[8:11], v7 offset:4640
	s_waitcnt lgkmcnt(1)
	v_mfma_f32_32x32x16_bf16 v[96:111], v[12:15], v[112:115], v[96:111]
	s_nop 8
	v_max_f32_e32 v4, v81, v81
	s_waitcnt lgkmcnt(0)
	v_mfma_f32_32x32x16_bf16 v[96:111], v[8:11], v[116:119], v[96:111]
	ds_read_b128 v[8:11], v7 offset:4672
	s_waitcnt lgkmcnt(0)
	v_mfma_f32_32x32x16_bf16 v[96:111], v[8:11], v[120:123], v[96:111]
	ds_read_b128 v[8:11], v7 offset:4704
	s_waitcnt lgkmcnt(0)
	v_mfma_f32_32x32x16_bf16 v[96:111], v[8:11], v[124:127], v[96:111]
	s_nop 11
	v_max3_f32 v7, v97, v82, v98
	v_max3_f32 v4, v4, v83, v99
	v_max3_f32 v7, v7, v80, v96
	v_max3_f32 v4, v4, v84, v100
	v_max3_f32 v7, v7, v85, v101
	v_max3_f32 v4, v4, v86, v102
	v_max3_f32 v7, v7, v87, v103
	v_max3_f32 v4, v4, v88, v104
	v_max3_f32 v7, v7, v89, v105
	v_max3_f32 v4, v4, v90, v106
	v_max3_f32 v7, v7, v91, v107
	v_max3_f32 v4, v4, v92, v108
	v_max3_f32 v7, v7, v93, v109
	v_max3_f32 v4, v4, v94, v110
	v_max3_f32 v7, v7, v95, v111
	v_max_f32_e32 v4, v4, v7
	ds_bpermute_b32 v7, v174, v4
	s_waitcnt lgkmcnt(0)
	v_max_f32_e32 v7, v7, v7
	v_max_f32_e32 v4, v4, v7
	v_cmp_lt_f32_e32 vcc, s38, v4
	s_cbranch_scc0 .LBB0_700
	s_cmp_lg_u64 vcc, 0
	s_cselect_b64 s[20:21], -1, 0
	s_cbranch_execz .LBB0_701
	s_branch .LBB0_702
